# hand-written GEMM k-loops in all four GEMM phases + attention loop trimmed (DMA addresses advanced in registers, SALU LDS targets, persistent -mref seed block as MFMA C operand)
# speedup vs baseline: 1.0315x; 1.0104x over previous
.LBB0_842:
	s_or_b64 exec, exec, s[0:1]
	v_mov_b32_e32 v129, v113
	v_mul_u32_u24_e32 v5, v4, v151
	v_lshl_add_u64 v[6:7], v[0:1], 0, v[128:129]
	v_mov_b32_e32 v131, v113
	v_lshlrev_b32_e32 v8, 1, v5
	v_mov_b32_e32 v9, v113
	v_readfirstlane_b32 s0, v155
	v_add_u32_e32 v5, 0x4000, v155
	v_lshl_add_u64 v[6:7], v[6:7], 0, v[130:131]
	v_lshl_add_u64 v[10:11], v[2:3], 0, v[8:9]
	v_mov_b32_e32 v133, v113
	s_mov_b32 m0, s0
	v_readfirstlane_b32 s0, v5
	v_add_u32_e32 v5, 0x1000, v155
	v_lshl_add_u64 v[10:11], v[10:11], 0, v[132:133]
	global_load_lds_dwordx4 v[6:7], off
	s_mov_b32 m0, s0
	v_readfirstlane_b32 s0, v5
	v_add_u32_e32 v5, 0x5000, v155
	global_load_lds_dwordx4 v[10:11], off
	v_lshl_add_u64 v[12:13], v[6:7], 0, s[34:35]
	s_mov_b32 m0, s0
	v_lshlrev_b32_e32 v112, 6, v4
	v_readfirstlane_b32 s0, v5
	v_add_u32_e32 v5, 0x2000, v155
	global_load_lds_dwordx4 v[12:13], off
	v_lshl_add_u64 v[10:11], v[10:11], 0, v[112:113]
	s_mov_b32 m0, s0
	v_readfirstlane_b32 s0, v5
	v_add_u32_e32 v5, 0x6000, v155
	global_load_lds_dwordx4 v[10:11], off
	v_lshl_add_u64 v[12:13], v[6:7], 0, s[36:37]
	s_mov_b32 m0, s0
	v_readfirstlane_b32 s0, v5
	v_add_u32_e32 v5, 0x3000, v155
	global_load_lds_dwordx4 v[12:13], off
	v_lshl_add_u64 v[10:11], v[10:11], 0, v[112:113]
	s_mov_b32 m0, s0
	v_readfirstlane_b32 s0, v5
	v_add_u32_e32 v5, 0x7000, v155
	global_load_lds_dwordx4 v[10:11], off
	v_lshl_add_u64 v[6:7], v[6:7], 0, s[38:39]
	s_mov_b32 m0, s0
	v_readfirstlane_b32 s0, v5
	global_load_lds_dwordx4 v[6:7], off
	v_lshl_add_u64 v[6:7], v[10:11], 0, v[112:113]
	s_mov_b32 m0, s0
	v_lshl_add_u64 v[140:141], v[0:1], 0, v[120:121]
	global_load_lds_dwordx4 v[6:7], off
	v_lshl_add_u64 v[0:1], v[2:3], 0, v[122:123]
	v_mov_b32_e32 v14, v113
	v_mov_b32_e32 v15, v113
	v_lshl_add_u64 v[142:143], v[0:1], 0, v[8:9]
	v_lshlrev_b32_e32 v146, 7, v4
	v_mul_hi_u32_u24_e32 v149, 0xc0, v4
	v_mul_u32_u24_e32 v148, 0xc0, v4
	v_mov_b32_e32 v0, v113
	v_mov_b32_e32 v1, v113
	v_mov_b32_e32 v2, v113
	v_mov_b32_e32 v3, v113
	v_mov_b32_e32 v4, v113
	v_mov_b32_e32 v5, v113
	v_mov_b32_e32 v6, v113
	v_mov_b32_e32 v7, v113
	v_mov_b32_e32 v8, v113
	v_mov_b32_e32 v10, v113
	v_mov_b32_e32 v11, v113
	v_mov_b32_e32 v12, v113
	v_mov_b32_e32 v13, v113
	v_mov_b64_e32 v[30:31], v[14:15]
	v_mov_b64_e32 v[46:47], v[14:15]
	v_mov_b64_e32 v[62:63], v[14:15]
	s_xor_b64 s[46:47], s[8:9], -1
	v_cmp_lt_u32_e64 s[8:9], v145, v127
	v_cmp_ge_u32_e64 s[10:11], v145, v127
	s_mov_b32 s33, 1
	v_mov_b32_e32 v147, v113
	v_lshlrev_b32_e32 v129, 6, v137
	v_mov_b64_e32 v[28:29], v[12:13]
	v_mov_b64_e32 v[26:27], v[10:11]
	v_mov_b64_e32 v[24:25], v[8:9]
	v_mov_b64_e32 v[22:23], v[6:7]
	v_mov_b64_e32 v[20:21], v[4:5]
	v_mov_b64_e32 v[18:19], v[2:3]
	v_mov_b64_e32 v[16:17], v[0:1]
	v_mov_b64_e32 v[44:45], v[12:13]
	v_mov_b64_e32 v[42:43], v[10:11]
	v_mov_b64_e32 v[40:41], v[8:9]
	v_mov_b64_e32 v[38:39], v[6:7]
	v_mov_b64_e32 v[36:37], v[4:5]
	v_mov_b64_e32 v[34:35], v[2:3]
	v_mov_b64_e32 v[32:33], v[0:1]
	v_mov_b64_e32 v[60:61], v[12:13]
	v_mov_b64_e32 v[58:59], v[10:11]
	v_mov_b64_e32 v[56:57], v[8:9]
	v_mov_b64_e32 v[54:55], v[6:7]
	v_mov_b64_e32 v[52:53], v[4:5]
	v_mov_b64_e32 v[50:51], v[2:3]
	v_mov_b64_e32 v[48:49], v[0:1]
	v_mov_b32_e32 v131, 0
	s_waitcnt vmcnt(0)
	v_mov_b64_e32 v[200:201], v[140:141]
	v_lshl_add_u64 v[202:203], v[140:141], 0, s[34:35]
	v_lshl_add_u64 v[204:205], v[140:141], 0, s[36:37]
	v_lshl_add_u64 v[206:207], v[140:141], 0, s[38:39]
	v_mov_b64_e32 v[208:209], v[142:143]
	v_lshl_add_u64 v[210:211], v[142:143], 0, v[112:113]
	v_lshl_add_u64 v[212:213], v[142:143], 0, v[146:147]
	v_lshl_add_u64 v[214:215], v[142:143], 0, v[148:149]
	v_readfirstlane_b32 s60, v155
	v_xor_b32_e32 v232, 0x80000000, v125
	v_mov_b32_e32 v233, v232
	v_mov_b32_e32 v234, v232
	v_mov_b32_e32 v235, v232
	v_mov_b32_e32 v236, v232
	v_mov_b32_e32 v237, v232
	v_mov_b32_e32 v238, v232
	v_mov_b32_e32 v239, v232
	v_mov_b32_e32 v240, v232
	v_mov_b32_e32 v241, v232
	v_mov_b32_e32 v242, v232
	v_mov_b32_e32 v243, v232
	v_mov_b32_e32 v244, v232
	v_mov_b32_e32 v245, v232
	v_mov_b32_e32 v246, v232
	v_mov_b32_e32 v247, v232
	s_branch .LBB0_845

.LBB0_845:
	s_waitcnt vmcnt(0)
	s_waitcnt lgkmcnt(0)
	s_add_i32 s0, s33, -1
	s_and_b32 s50, s0, 1
	v_cmp_lt_u32_e32 vcc, s33, v137
	s_barrier
	s_and_saveexec_b64 s[0:1], vcc
	s_cbranch_execz .LBB0_847
	s_lshl_b32 s48, s50, 15
	s_xor_b32 s48, s48, 0x8000
	s_add_u32 s48, s48, s60
	s_mov_b32 m0, s48
	s_nop 0
	global_load_lds_dwordx4 v[200:201], off
	s_add_u32 m0, s48, 0x4000
	v_lshl_add_u64 v[200:201], v[200:201], 0, s[28:29]
	global_load_lds_dwordx4 v[208:209], off
	s_add_u32 m0, s48, 0x1000
	v_lshl_add_u64 v[208:209], v[208:209], 0, s[40:41]
	global_load_lds_dwordx4 v[202:203], off
	s_add_u32 m0, s48, 0x5000
	v_lshl_add_u64 v[202:203], v[202:203], 0, s[28:29]
	global_load_lds_dwordx4 v[210:211], off
	s_add_u32 m0, s48, 0x2000
	v_lshl_add_u64 v[210:211], v[210:211], 0, s[40:41]
	global_load_lds_dwordx4 v[204:205], off
	s_add_u32 m0, s48, 0x6000
	v_lshl_add_u64 v[204:205], v[204:205], 0, s[28:29]
	global_load_lds_dwordx4 v[212:213], off
	s_add_u32 m0, s48, 0x3000
	v_lshl_add_u64 v[212:213], v[212:213], 0, s[40:41]
	global_load_lds_dwordx4 v[206:207], off
	s_add_u32 m0, s48, 0x7000
	v_lshl_add_u64 v[206:207], v[206:207], 0, s[28:29]
	global_load_lds_dwordx4 v[214:215], off
	v_lshl_add_u64 v[214:215], v[214:215], 0, s[40:41]
.LBB0_847:
	s_or_b64 exec, exec, s[0:1]
	v_add_u32_e32 v133, 64, v172
	s_and_saveexec_b64 s[0:1], s[10:11]
	s_xor_b64 s[0:1], exec, s[0:1]
	v_add_u32_e32 v133, 64, v172
	s_andn2_saveexec_b64 s[48:49], s[0:1]
	s_cbranch_execz .LBB0_844
	s_lshl_b32 s0, s50, 15
	s_add_i32 s58, s0, 0
	v_add_u32_e32 v173, s58, v152
	v_add_u32_e32 v80, v173, v156
	ds_read_b128 v[174:177], v80
	ds_read_b128 v[178:181], v80 offset:8192
	v_add_u32_e32 v182, v173, v157
	v_add_u32_e32 v186, v173, v158
	s_waitcnt lgkmcnt(0)
	v_mfma_f32_32x32x16_bf16 v[80:95], v[174:177], v[96:99], v[232:247]
	ds_read_b128 v[174:177], v182
	ds_read_b128 v[182:185], v182 offset:8192
	v_add_u32_e32 v173, v173, v159
	v_cmp_gt_u32_e32 vcc, v133, v171
	v_mfma_f32_32x32x16_bf16 v[64:79], v[178:181], v[96:99], v[232:247]
	s_waitcnt lgkmcnt(0)
	v_mfma_f32_32x32x16_bf16 v[80:95], v[174:177], v[100:103], v[80:95]
	ds_read_b128 v[174:177], v186
	ds_read_b128 v[186:189], v186 offset:8192
	v_mfma_f32_32x32x16_bf16 v[64:79], v[182:185], v[100:103], v[64:79]
	s_waitcnt lgkmcnt(0)
	v_mfma_f32_32x32x16_bf16 v[80:95], v[174:177], v[104:107], v[80:95]
	ds_read_b128 v[174:177], v173
	ds_read_b128 v[190:193], v173 offset:8192
	v_mfma_f32_32x32x16_bf16 v[64:79], v[186:189], v[104:107], v[64:79]
	s_waitcnt lgkmcnt(0)
	v_mfma_f32_32x32x16_bf16 v[80:95], v[174:177], v[108:111], v[80:95]
	v_mfma_f32_32x32x16_bf16 v[64:79], v[190:193], v[108:111], v[64:79]
	s_and_saveexec_b64 s[50:51], vcc
	s_cbranch_execz .LBB0_852
	v_add_u32_e32 v172, v114, v172
	v_add_u32_e32 v173, 1, v172
	v_cmp_lt_u32_e32 vcc, v172, v171
	v_cmp_lt_u32_e64 s[0:1], v173, v171
	s_or_b64 vcc, s[0:1], vcc
	v_add_u32_e32 v173, 2, v172
	s_nop 2
	v_cndmask_b32_e32 v80, v169, v80, vcc
	v_cmp_lt_u32_e32 vcc, v173, v171
	v_add_u32_e32 v173, 3, v172
	v_cndmask_b32_e64 v81, v169, v81, s[0:1]
	v_cndmask_b32_e32 v82, v169, v82, vcc
	v_cmp_lt_u32_e32 vcc, v173, v171
	v_add_u32_e32 v173, 4, v172
	s_nop 0
	v_cndmask_b32_e32 v83, v169, v83, vcc
	v_cmp_lt_u32_e32 vcc, v173, v171
	v_add_u32_e32 v173, 5, v172
	s_nop 0
	v_cndmask_b32_e32 v84, v169, v84, vcc
	v_cmp_lt_u32_e32 vcc, v173, v171
	v_add_u32_e32 v173, 6, v172
	s_nop 0
	v_cndmask_b32_e32 v85, v169, v85, vcc
	v_cmp_lt_u32_e32 vcc, v173, v171
	v_add_u32_e32 v173, 7, v172
	s_nop 0
	v_cndmask_b32_e32 v86, v169, v86, vcc
	v_cmp_lt_u32_e32 vcc, v173, v171
	v_add_u32_e32 v173, 16, v172
	s_nop 0
	v_cndmask_b32_e32 v87, v169, v87, vcc
	v_cmp_lt_u32_e32 vcc, v173, v171
	v_add_u32_e32 v173, 17, v172
	s_nop 0
	v_cndmask_b32_e32 v88, v169, v88, vcc
	v_cmp_lt_u32_e32 vcc, v173, v171
	v_add_u32_e32 v173, 18, v172
	s_nop 0
	v_cndmask_b32_e32 v89, v169, v89, vcc
	v_cmp_lt_u32_e32 vcc, v173, v171
	v_add_u32_e32 v173, 19, v172
	s_nop 0
	v_cndmask_b32_e32 v90, v169, v90, vcc
	v_cmp_lt_u32_e32 vcc, v173, v171
	v_add_u32_e32 v173, 20, v172
	s_nop 0
	v_cndmask_b32_e32 v91, v169, v91, vcc
	v_cmp_lt_u32_e32 vcc, v173, v171
	v_add_u32_e32 v173, 21, v172
	s_nop 0
	v_cndmask_b32_e32 v92, v169, v92, vcc
	v_cmp_lt_u32_e32 vcc, v173, v171
	v_add_u32_e32 v173, 22, v172
	s_nop 0
	v_cndmask_b32_e32 v93, v169, v93, vcc
	v_cmp_lt_u32_e32 vcc, v173, v171
	v_add_u32_e32 v173, 23, v172
	s_nop 0
	v_cndmask_b32_e32 v94, v169, v94, vcc
	v_cmp_lt_u32_e32 vcc, v173, v171
	v_add_u32_e32 v173, 32, v172
	v_cmp_lt_u32_e64 s[0:1], v173, v171
	s_or_b64 vcc, s[0:1], vcc
	v_add_u32_e32 v173, 33, v172
	v_cndmask_b32_e32 v95, v169, v95, vcc
	v_cmp_lt_u32_e32 vcc, v173, v171
	v_add_u32_e32 v173, 34, v172
	v_cndmask_b32_e64 v64, v169, v64, s[0:1]
	v_cndmask_b32_e32 v65, v169, v65, vcc
	v_cmp_lt_u32_e32 vcc, v173, v171
	v_add_u32_e32 v173, 35, v172
	s_nop 0
	v_cndmask_b32_e32 v66, v169, v66, vcc
	v_cmp_lt_u32_e32 vcc, v173, v171
	v_add_u32_e32 v173, 36, v172
	s_nop 0
	v_cndmask_b32_e32 v67, v169, v67, vcc
	v_cmp_lt_u32_e32 vcc, v173, v171
	v_add_u32_e32 v173, 37, v172
	s_nop 0
	v_cndmask_b32_e32 v68, v169, v68, vcc
	v_cmp_lt_u32_e32 vcc, v173, v171
	v_add_u32_e32 v173, 38, v172
	s_nop 0
	v_cndmask_b32_e32 v69, v169, v69, vcc
	v_cmp_lt_u32_e32 vcc, v173, v171
	v_add_u32_e32 v173, 39, v172
	s_nop 0
	v_cndmask_b32_e32 v70, v169, v70, vcc
	v_cmp_lt_u32_e32 vcc, v173, v171
	v_add_u32_e32 v173, 48, v172
	s_nop 0
	v_cndmask_b32_e32 v71, v169, v71, vcc
	v_cmp_lt_u32_e32 vcc, v173, v171
	v_add_u32_e32 v173, 49, v172
	s_nop 0
	v_cndmask_b32_e32 v72, v169, v72, vcc
	v_cmp_lt_u32_e32 vcc, v173, v171
	v_add_u32_e32 v173, 50, v172
	s_nop 0
	v_cndmask_b32_e32 v73, v169, v73, vcc
	v_cmp_lt_u32_e32 vcc, v173, v171
	v_add_u32_e32 v173, 51, v172
	s_nop 0
	v_cndmask_b32_e32 v74, v169, v74, vcc
	v_cmp_lt_u32_e32 vcc, v173, v171
	v_add_u32_e32 v173, 52, v172
	s_nop 0
	v_cndmask_b32_e32 v75, v169, v75, vcc
	v_cmp_lt_u32_e32 vcc, v173, v171
	v_add_u32_e32 v173, 53, v172
	s_nop 0
	v_cndmask_b32_e32 v76, v169, v76, vcc
	v_cmp_lt_u32_e32 vcc, v173, v171
	v_add_u32_e32 v173, 54, v172
	v_add_u32_e32 v172, 55, v172
	v_cndmask_b32_e32 v77, v169, v77, vcc
	v_cmp_lt_u32_e32 vcc, v173, v171
	s_nop 1
	v_cndmask_b32_e32 v78, v169, v78, vcc
	v_cmp_lt_u32_e32 vcc, v172, v171
	s_nop 1
	v_cndmask_b32_e32 v79, v169, v79, vcc
.LBB0_852:
	s_or_b64 exec, exec, s[50:51]
	s_and_saveexec_b64 s[0:1], s[46:47]
	s_cbranch_execz .LBB0_843
	s_nop 5
	v_max_f32_e32 v172, v81, v81
	v_max_f32_e32 v173, v80, v80
	v_max_f32_e32 v172, v173, v172
	v_max3_f32 v172, v172, v82, v83
	v_max3_f32 v172, v172, v84, v85
	v_max3_f32 v172, v172, v86, v87
	v_max3_f32 v172, v172, v88, v89
	v_max3_f32 v172, v172, v90, v91
	v_max3_f32 v172, v172, v92, v93
	v_max3_f32 v172, v172, v94, v95
	v_max3_f32 v172, v172, v64, v65
	v_max3_f32 v172, v172, v66, v67
	v_max3_f32 v172, v172, v68, v69
	v_max3_f32 v172, v172, v70, v71
	v_max3_f32 v172, v172, v72, v73
	v_max3_f32 v172, v172, v74, v75
	v_max3_f32 v172, v172, v76, v77
	v_max3_f32 v172, v172, v78, v79
	ds_bpermute_b32 v173, v115, v172
	s_waitcnt lgkmcnt(0)
	v_max_f32_e32 v173, v173, v173
	v_max_f32_e32 v172, v172, v173
	v_cmp_gt_f32_e64 vcc, |v172|, s12
	s_cbranch_vccz .LBB0_843
	v_exp_f32_e64 v174, -v172
	v_add_f32_e32 v125, v125, v172
	s_nop 0
	v_xor_b32_e32 v232, 0x80000000, v125
	v_mov_b32_e32 v233, v232
	v_mov_b32_e32 v234, v232
	v_mov_b32_e32 v235, v232
	v_mov_b32_e32 v236, v232
	v_mov_b32_e32 v237, v232
	v_mov_b32_e32 v238, v232
	v_mov_b32_e32 v239, v232
	v_mov_b32_e32 v240, v232
	v_mov_b32_e32 v241, v232
	v_mov_b32_e32 v242, v232
	v_mov_b32_e32 v243, v232
	v_mov_b32_e32 v244, v232
	v_mov_b32_e32 v245, v232
	v_mov_b32_e32 v246, v232
	v_mov_b32_e32 v247, v232
	v_sub_f32_e32 v79, v79, v172
	v_sub_f32_e32 v78, v78, v172
	v_pk_mul_f32 v[62:63], v[62:63], v[174:175] op_sel_hi:[1,0]
	v_pk_mul_f32 v[60:61], v[60:61], v[174:175] op_sel_hi:[1,0]
	v_pk_mul_f32 v[58:59], v[58:59], v[174:175] op_sel_hi:[1,0]
	v_pk_mul_f32 v[56:57], v[56:57], v[174:175] op_sel_hi:[1,0]
	v_pk_mul_f32 v[54:55], v[54:55], v[174:175] op_sel_hi:[1,0]
	v_pk_mul_f32 v[52:53], v[52:53], v[174:175] op_sel_hi:[1,0]
	v_pk_mul_f32 v[50:51], v[50:51], v[174:175] op_sel_hi:[1,0]
	v_pk_mul_f32 v[48:49], v[48:49], v[174:175] op_sel_hi:[1,0]
	v_pk_mul_f32 v[46:47], v[46:47], v[174:175] op_sel_hi:[1,0]
	v_pk_mul_f32 v[44:45], v[44:45], v[174:175] op_sel_hi:[1,0]
	v_pk_mul_f32 v[42:43], v[42:43], v[174:175] op_sel_hi:[1,0]
	v_pk_mul_f32 v[40:41], v[40:41], v[174:175] op_sel_hi:[1,0]
	v_pk_mul_f32 v[38:39], v[38:39], v[174:175] op_sel_hi:[1,0]
	v_pk_mul_f32 v[36:37], v[36:37], v[174:175] op_sel_hi:[1,0]
	v_pk_mul_f32 v[34:35], v[34:35], v[174:175] op_sel_hi:[1,0]
	v_pk_mul_f32 v[32:33], v[32:33], v[174:175] op_sel_hi:[1,0]
	v_pk_mul_f32 v[30:31], v[30:31], v[174:175] op_sel_hi:[1,0]
	v_pk_mul_f32 v[28:29], v[28:29], v[174:175] op_sel_hi:[1,0]
	v_pk_mul_f32 v[26:27], v[26:27], v[174:175] op_sel_hi:[1,0]
	v_pk_mul_f32 v[24:25], v[24:25], v[174:175] op_sel_hi:[1,0]
	v_pk_mul_f32 v[22:23], v[22:23], v[174:175] op_sel_hi:[1,0]
	v_pk_mul_f32 v[20:21], v[20:21], v[174:175] op_sel_hi:[1,0]
	v_pk_mul_f32 v[18:19], v[18:19], v[174:175] op_sel_hi:[1,0]
	v_pk_mul_f32 v[16:17], v[16:17], v[174:175] op_sel_hi:[1,0]
	v_pk_mul_f32 v[14:15], v[14:15], v[174:175] op_sel_hi:[1,0]
	v_pk_mul_f32 v[12:13], v[12:13], v[174:175] op_sel_hi:[1,0]
	v_pk_mul_f32 v[10:11], v[10:11], v[174:175] op_sel_hi:[1,0]
	v_pk_mul_f32 v[8:9], v[8:9], v[174:175] op_sel_hi:[1,0]
	v_pk_mul_f32 v[6:7], v[6:7], v[174:175] op_sel_hi:[1,0]
	v_pk_mul_f32 v[4:5], v[4:5], v[174:175] op_sel_hi:[1,0]
	v_pk_mul_f32 v[2:3], v[2:3], v[174:175] op_sel_hi:[1,0]
	v_pk_mul_f32 v[0:1], v[0:1], v[174:175] op_sel_hi:[1,0]
	v_sub_f32_e32 v77, v77, v172
	v_sub_f32_e32 v76, v76, v172
	v_sub_f32_e32 v75, v75, v172
	v_sub_f32_e32 v74, v74, v172
	v_sub_f32_e32 v73, v73, v172
	v_sub_f32_e32 v72, v72, v172
	v_sub_f32_e32 v71, v71, v172
	v_sub_f32_e32 v70, v70, v172
	v_sub_f32_e32 v69, v69, v172
	v_sub_f32_e32 v68, v68, v172
	v_sub_f32_e32 v67, v67, v172
	v_sub_f32_e32 v66, v66, v172
	v_sub_f32_e32 v65, v65, v172
	v_sub_f32_e32 v64, v64, v172
	v_sub_f32_e32 v95, v95, v172
	v_sub_f32_e32 v94, v94, v172
	v_sub_f32_e32 v93, v93, v172
	v_sub_f32_e32 v92, v92, v172
	v_sub_f32_e32 v91, v91, v172
	v_sub_f32_e32 v90, v90, v172
	v_sub_f32_e32 v89, v89, v172
	v_sub_f32_e32 v88, v88, v172
	v_sub_f32_e32 v87, v87, v172
	v_sub_f32_e32 v86, v86, v172
	v_sub_f32_e32 v85, v85, v172
	v_sub_f32_e32 v84, v84, v172
	v_sub_f32_e32 v83, v83, v172
	v_sub_f32_e32 v82, v82, v172
	v_sub_f32_e32 v81, v81, v172
	v_sub_f32_e32 v80, v80, v172
	v_mul_f32_e32 v131, v131, v174
	s_branch .LBB0_843
